# P6 QH/VH loads via base+offset immediates (on top of v020)
# baseline (speedup 1.0000x reference)
; __device__ __forceinline__ void hg_gates(const float* ZF, const float* LB, int c, int h, int d, int seg, float (&lf)[32], float (&kk)[32], float& pre, float& tot, float& ref, LAS float* SEG) {
;     ...
;     for (int i = 0; i < 32; ++i) { const bool valid = 128 * c + 32 * seg + i >= 112; const float z = fminf(fmaxf(zr[i], -30.f), 30.f);
;         const float en = __expf(-z), sg = __builtin_amdgcn_rcpf(1.0f + en); lf[i] = valid ? __logf(lb + (1.0f - lb) * sg) : 0.f; kk[i] = valid ? (1.0f - lb) * en * sg : 0.f;
; __global__ void __launch_bounds__(NT, 2) hymba_fwd(Args args) {
;     ...
;             unsigned qr[32], vr[32]; const float eref = __expf(ref);
; #pragma unroll
;             for (int i = 0; i < 32; ++i) { const size_t g = (size_t)(rbase + 32 * seg + i) * 512 + h * 128 + d; qr[i] = __builtin_nontemporal_load(QH + g); vr[i] = __builtin_nontemporal_load(VH + g); }
.LBB0_1129:
	s_or_b64 exec, exec, s[50:51]
	v_mul_f32_e32 v1, v15, v5
	v_mul_f32_e32 v1, v1, v7
	v_cndmask_b32_e64 v95, 0, v1, s[4:5]
	v_mul_f32_e32 v1, v15, v3
	v_mul_f32_e32 v1, v1, v9
	v_cndmask_b32_e64 v93, 0, v1, s[70:71]
	v_mul_f32_e32 v1, v15, v11
	v_mul_f32_e32 v1, v1, v13
	v_cndmask_b32_e64 v91, 0, v1, s[72:73]
	v_mul_f32_e32 v1, v15, v19
	v_mul_f32_e32 v1, v1, v21
	v_cndmask_b32_e64 v89, 0, v1, s[74:75]
	v_mul_f32_e32 v1, v15, v23
	v_mul_f32_e32 v1, v1, v25
	v_cndmask_b32_e64 v87, 0, v1, s[76:77]
	v_mul_f32_e32 v1, v15, v31
	v_mul_f32_e32 v1, v1, v51
	v_cndmask_b32_e64 v3, 0, v1, s[78:79]
	v_mul_f32_e32 v1, v15, v55
	v_mul_f32_e32 v1, v1, v67
	v_cndmask_b32_e64 v85, 0, v1, s[80:81]
	v_mul_f32_e32 v1, v15, v71
	v_mul_f32_e32 v1, v1, v73
	v_cndmask_b32_e64 v83, 0, v1, s[82:83]
	v_mul_f32_e32 v1, v15, v77
	v_mul_f32_e32 v1, v1, v79
	v_cndmask_b32_e64 v81, 0, v1, s[84:85]
	v_mul_f32_e32 v1, v15, v94
	v_mul_f32_e32 v1, v1, v99
	v_cndmask_b32_e64 v5, 0, v1, s[86:87]
	v_mul_f32_e32 v1, v15, v157
	v_mul_f32_e32 v1, v1, v158
	v_cndmask_b32_e64 v79, 0, v1, s[88:89]
	v_mul_f32_e32 v1, v15, v159
	v_mul_f32_e32 v1, v1, v160
	v_cndmask_b32_e64 v77, 0, v1, s[90:91]
	v_mul_f32_e32 v1, v15, v161
	v_mul_f32_e32 v1, v1, v162
	v_cndmask_b32_e64 v75, 0, v1, s[92:93]
	v_mul_f32_e32 v1, v15, v163
	v_mul_f32_e32 v1, v1, v164
	v_cndmask_b32_e64 v7, 0, v1, s[94:95]
	v_mul_f32_e32 v1, v15, v165
	v_mul_f32_e32 v1, v1, v166
	v_cndmask_b32_e64 v73, 0, v1, s[96:97]
	v_mul_f32_e32 v1, v15, v167
	v_mul_f32_e32 v1, v1, v168
	v_cndmask_b32_e64 v71, 0, v1, s[0:1]
	v_mul_f32_e32 v1, v15, v169
	v_mul_f32_e32 v1, v1, v170
	v_cndmask_b32_e64 v69, 0, v1, s[6:7]
	v_mul_f32_e32 v1, v15, v171
	v_mul_f32_e32 v1, v1, v172
	v_cndmask_b32_e64 v9, 0, v1, s[8:9]
	v_mul_f32_e32 v1, v15, v173
	v_mul_f32_e32 v1, v1, v174
	v_cndmask_b32_e64 v67, 0, v1, s[10:11]
	v_mul_f32_e32 v1, v15, v175
	v_mul_f32_e32 v1, v1, v176
	v_cndmask_b32_e64 v55, 0, v1, s[12:13]
	v_mul_f32_e32 v1, v15, v177
	v_mul_f32_e32 v1, v1, v180
	v_cndmask_b32_e64 v53, 0, v1, s[14:15]
	v_mul_f32_e32 v1, v15, v181
	v_mul_f32_e32 v1, v1, v182
	v_cndmask_b32_e64 v11, 0, v1, s[16:17]
	v_mul_f32_e32 v1, v15, v183
	v_mul_f32_e32 v1, v1, v184
	v_cndmask_b32_e64 v51, 0, v1, s[18:19]
	v_mul_f32_e32 v1, v15, v185
	v_mul_f32_e32 v1, v1, v186
	v_cndmask_b32_e64 v31, 0, v1, s[20:21]
	v_mul_f32_e32 v1, v15, v187
	v_mul_f32_e32 v1, v1, v188
	v_cndmask_b32_e64 v29, 0, v1, s[22:23]
	v_mul_f32_e32 v1, v15, v189
	v_mul_f32_e32 v1, v1, v190
	v_cndmask_b32_e64 v13, 0, v1, s[24:25]
	v_mul_f32_e32 v1, v15, v191
	v_mul_f32_e32 v1, v1, v192
	v_cndmask_b32_e64 v27, 0, v1, s[26:27]
	v_mul_f32_e32 v1, v15, v193
	v_mul_f32_e32 v1, v1, v194
	v_cndmask_b32_e64 v25, 0, v1, s[28:29]
	v_mul_f32_e32 v1, v15, v195
	v_mul_f32_e32 v1, v1, v196
	v_cndmask_b32_e64 v23, 0, v1, s[30:31]
	v_mul_f32_e32 v1, v15, v197
	v_mul_f32_e32 v1, v1, v198
	v_cndmask_b32_e64 v21, 0, v1, s[34:35]
	v_mul_f32_e32 v1, v15, v199
	v_mul_f32_e32 v1, v1, v200
	v_cndmask_b32_e64 v19, 0, v1, s[36:37]
	v_mul_f32_e32 v1, v15, v201
	v_mul_f32_e32 v1, v1, v202
	v_cndmask_b32_e32 v17, 0, v1, vcc
	v_ashrrev_i32_e32 v1, 31, v0
	s_waitcnt lgkmcnt(0)
	v_mov_b32_e32 v99, v96
	v_mov_b32_e32 v15, v97
	v_lshlrev_b64 v[96:97], 9, v[0:1]
	v_or3_b32 v97, v97, 0, 0
	v_or3_b32 v96, v96, s67, v56
	v_readlane_b32 s0, v237, 33
	v_readlane_b32 s2, v237, 29
	v_lshlrev_b64 v[96:97], 1, v[96:97]
	v_readlane_b32 s1, v237, 34
	v_readlane_b32 s3, v237, 30
	v_pk_add_f32 v[14:15], v[98:99], v[14:15]
	v_lshl_add_u64 v[98:99], s[0:1], 0, v[96:97]
	v_lshl_add_u64 v[96:97], s[2:3], 0, v[96:97]
	s_mov_b32 s100, 0x2000
	s_mov_b32 s101, 0
	global_load_ushort v218, v[98:99], off nt
	global_load_ushort v214, v[96:97], off nt
	global_load_ushort v217, v[98:99], off offset:1024 nt
	global_load_ushort v216, v[96:97], off offset:1024 nt
	global_load_ushort v215, v[98:99], off offset:2048 nt
	global_load_ushort v1, v[96:97], off offset:2048 nt
	global_load_ushort v213, v[98:99], off offset:3072 nt
	global_load_ushort v212, v[96:97], off offset:3072 nt
	v_lshl_add_u64 v[98:99], v[98:99], 0, s[100:101]
	v_lshl_add_u64 v[96:97], v[96:97], 0, s[100:101]
	global_load_ushort v211, v[98:99], off offset:-4096 nt
	global_load_ushort v207, v[96:97], off offset:-4096 nt
	global_load_ushort v210, v[98:99], off offset:-3072 nt
	global_load_ushort v209, v[96:97], off offset:-3072 nt
	global_load_ushort v208, v[98:99], off offset:-2048 nt
	global_load_ushort v203, v[96:97], off offset:-2048 nt
	global_load_ushort v206, v[98:99], off offset:-1024 nt
	global_load_ushort v205, v[96:97], off offset:-1024 nt
	global_load_ushort v204, v[98:99], off nt
	global_load_ushort v199, v[96:97], off nt
	global_load_ushort v202, v[98:99], off offset:1024 nt
	global_load_ushort v201, v[96:97], off offset:1024 nt
	global_load_ushort v200, v[98:99], off offset:2048 nt
	global_load_ushort v195, v[96:97], off offset:2048 nt
	global_load_ushort v198, v[98:99], off offset:3072 nt
	global_load_ushort v197, v[96:97], off offset:3072 nt
	v_lshl_add_u64 v[98:99], v[98:99], 0, s[100:101]
	v_lshl_add_u64 v[96:97], v[96:97], 0, s[100:101]
	global_load_ushort v196, v[98:99], off offset:-4096 nt
	global_load_ushort v191, v[96:97], off offset:-4096 nt
	global_load_ushort v194, v[98:99], off offset:-3072 nt
	global_load_ushort v193, v[96:97], off offset:-3072 nt
	global_load_ushort v192, v[98:99], off offset:-2048 nt
	global_load_ushort v187, v[96:97], off offset:-2048 nt
	global_load_ushort v190, v[98:99], off offset:-1024 nt
	global_load_ushort v189, v[96:97], off offset:-1024 nt
	global_load_ushort v188, v[98:99], off nt
	global_load_ushort v183, v[96:97], off nt
; __device__ __forceinline__ unsigned cvtpk_s(float lo, float hi) { f32x2_t v = {lo, hi}; bf16x2_t b = __builtin_convertvector(v, bf16x2_t); return __builtin_bit_cast(unsigned, b); }
; __global__ void __launch_bounds__(NT, 2) hymba_fwd(Args args) {
;     ...
;             for (int i = 0; i < 32; ++i) { const size_t g = (size_t)(rbase + 32 * seg + i) * 512 + h * 128 + d; qr[i] = __builtin_nontemporal_load(QH + g); vr[i] = __builtin_nontemporal_load(VH + g); }
; #pragma unroll
;             for (int i = 0; i < 32; ++i) { const int s = 32 * seg + i;
;                 run += lf[i]; const float q = bf2f((unsigned short)qr[i]);
;                 { const float e1 = __expf(fminf(fmaxf(run - ref, -80.f), 80.f)), qt = q * e1; const unsigned pa = cvtpk_s(qt, kk[i] * __builtin_amdgcn_rcpf(e1)), pb = cvtpk_s(qt * eref, 0.f); X0[s * XP + d] = (bf16)pa; X1[s * XP + d] = (bf16)(pa >> 16); X2[s * XP + d] = (bf16)pb; }
;                 const unsigned v = vr[i]; if (i & 1) vp[i >> 1] |= v << 16; else vp[i >> 1] = v; }
	global_load_ushort v186, v[98:99], off offset:1024 nt
	global_load_ushort v185, v[96:97], off offset:1024 nt
	global_load_ushort v184, v[98:99], off offset:2048 nt
	global_load_ushort v177, v[96:97], off offset:2048 nt
	global_load_ushort v182, v[98:99], off offset:3072 nt
	global_load_ushort v181, v[96:97], off offset:3072 nt
	v_lshl_add_u64 v[98:99], v[98:99], 0, s[100:101]
	v_lshl_add_u64 v[96:97], v[96:97], 0, s[100:101]
	global_load_ushort v180, v[98:99], off offset:-4096 nt
	global_load_ushort v173, v[96:97], off offset:-4096 nt
	global_load_ushort v176, v[98:99], off offset:-3072 nt
	global_load_ushort v175, v[96:97], off offset:-3072 nt
	global_load_ushort v174, v[98:99], off offset:-2048 nt
	global_load_ushort v169, v[96:97], off offset:-2048 nt
	global_load_ushort v172, v[98:99], off offset:-1024 nt
	global_load_ushort v171, v[96:97], off offset:-1024 nt
	global_load_ushort v170, v[98:99], off nt
	global_load_ushort v165, v[96:97], off nt
	global_load_ushort v168, v[98:99], off offset:1024 nt
	global_load_ushort v167, v[96:97], off offset:1024 nt
	global_load_ushort v166, v[98:99], off offset:2048 nt
	global_load_ushort v161, v[96:97], off offset:2048 nt
	global_load_ushort v164, v[98:99], off offset:3072 nt
	global_load_ushort v163, v[96:97], off offset:3072 nt
	v_lshl_add_u64 v[98:99], v[98:99], 0, s[100:101]
	v_lshl_add_u64 v[96:97], v[96:97], 0, s[100:101]
	global_load_ushort v162, v[98:99], off offset:-4096 nt
	global_load_ushort v157, v[96:97], off offset:-4096 nt
	global_load_ushort v160, v[98:99], off offset:-3072 nt
	global_load_ushort v159, v[96:97], off offset:-3072 nt
	global_load_ushort v158, v[98:99], off offset:-2048 nt
	v_mul_f32_e32 v94, 0x3fb8aa3b, v15
	v_mov_b32_e32 v220, v96
	v_mov_b32_e32 v221, v97
	global_load_ushort v96, v[220:221], off offset:-2048 nt
	v_sub_f32_e32 v0, v14, v15
	v_med3_f32 v0, v0, s63, v152
	v_mul_f32_e32 v0, 0x3fb8aa3b, v0
	global_load_ushort v99, v[98:99], off offset:-1024 nt
	s_waitcnt vmcnt(62)
	v_lshlrev_b32_e32 v218, 16, v218
	global_load_ushort v97, v[220:221], off offset:-1024 nt
	v_exp_f32_e32 v98, v94
	v_exp_f32_e32 v94, v0
	v_add_f32_e32 v14, v14, v92
	s_waitcnt vmcnt(56)
	v_lshl_or_b32 v1, v212, 16, v1
	v_rcp_f32_e32 v219, v94
	s_nop 0
	v_pk_mul_f32 v[94:95], v[94:95], v[218:219]
	s_nop 0
	v_cvt_pk_bf16_f32 v0, v94, v95
	v_mul_f32_e32 v94, v98, v94
	v_cvt_pk_bf16_f32 v94, v94, s0
	ds_write_b16 v106, v0
	ds_write_b16_d16_hi v106, v0 offset:34816
	ds_write_b16 v107, v94
	v_sub_f32_e32 v0, v14, v15
	v_med3_f32 v0, v0, s63, v152
	v_mul_f32_e32 v0, 0x3fb8aa3b, v0
	v_exp_f32_e32 v92, v0
	v_add_f32_e32 v14, v14, v90
	v_sub_f32_e32 v90, v14, v15
	v_med3_f32 v90, v90, s63, v152
	v_rcp_f32_e32 v95, v92
	v_mul_f32_e32 v90, 0x3fb8aa3b, v90
	v_exp_f32_e32 v90, v90
	v_lshlrev_b32_e32 v94, 16, v217
	v_add_f32_e32 v14, v14, v88
	v_pk_mul_f32 v[92:93], v[92:93], v[94:95]
	v_sub_f32_e32 v88, v14, v15
	v_cvt_pk_bf16_f32 v0, v92, v93
	v_rcp_f32_e32 v93, v90
	v_med3_f32 v88, v88, s63, v152
	v_mul_f32_e32 v92, v98, v92
	v_mul_f32_e32 v88, 0x3fb8aa3b, v88
	v_cvt_pk_bf16_f32 v92, v92, s0
	v_exp_f32_e32 v88, v88
	ds_write_b16 v106, v0 offset:272
	ds_write_b16_d16_hi v106, v0 offset:35088
	ds_write_b16 v108, v92
	v_lshlrev_b32_e32 v92, 16, v215
	v_pk_mul_f32 v[90:91], v[90:91], v[92:93]
	v_add_f32_e32 v14, v14, v86
	v_cvt_pk_bf16_f32 v91, v90, v91
	v_mul_f32_e32 v90, v98, v90
	v_sub_f32_e32 v86, v14, v15
	v_cvt_pk_bf16_f32 v90, v90, s0
	ds_write_b16 v106, v91 offset:544
	ds_write_b16_d16_hi v106, v91 offset:35360
	ds_write_b16 v109, v90
	v_rcp_f32_e32 v91, v88
	v_med3_f32 v86, v86, s63, v152
	v_mul_f32_e32 v86, 0x3fb8aa3b, v86
	v_exp_f32_e32 v86, v86
	v_lshlrev_b32_e32 v90, 16, v213
	v_pk_mul_f32 v[88:89], v[88:89], v[90:91]
	v_add_f32_e32 v14, v14, v2
	v_cvt_pk_bf16_f32 v89, v88, v89
	v_mul_f32_e32 v88, v98, v88
	v_sub_f32_e32 v2, v14, v15
	v_cvt_pk_bf16_f32 v88, v88, s0
	ds_write_b16 v106, v89 offset:816
	ds_write_b16_d16_hi v106, v89 offset:35632
	ds_write_b16 v110, v88
	v_rcp_f32_e32 v89, v86
	v_med3_f32 v2, v2, s63, v152
	v_mul_f32_e32 v2, 0x3fb8aa3b, v2
	v_exp_f32_e32 v2, v2
	s_waitcnt vmcnt(55)
	v_lshlrev_b32_e32 v88, 16, v211
	v_pk_mul_f32 v[86:87], v[86:87], v[88:89]
	v_lshl_or_b32 v0, v216, 16, v214
	v_cvt_pk_bf16_f32 v87, v86, v87
	v_mul_f32_e32 v86, v98, v86
	v_cvt_pk_bf16_f32 v86, v86, s0
	ds_write_b16 v106, v87 offset:1088
	ds_write_b16_d16_hi v106, v87 offset:35904
	ds_write_b16 v111, v86
	v_rcp_f32_e32 v87, v2
	s_waitcnt vmcnt(53)
	v_lshlrev_b32_e32 v86, 16, v210
	v_pk_mul_f32 v[2:3], v[2:3], v[86:87]
	s_nop 0
	v_cvt_pk_bf16_f32 v3, v2, v3
	v_mul_f32_e32 v2, v98, v2
	v_cvt_pk_bf16_f32 v2, v2, s0
	ds_write_b16 v106, v3 offset:1360
	ds_write_b16_d16_hi v106, v3 offset:36176
	ds_write_b16 v112, v2
	v_add_f32_e32 v3, v14, v84
	v_sub_f32_e32 v14, v3, v15
	v_med3_f32 v14, v14, s63, v152
	v_mul_f32_e32 v14, 0x3fb8aa3b, v14
	v_exp_f32_e32 v84, v14
	s_waitcnt vmcnt(51)
	v_lshlrev_b32_e32 v86, 16, v208
	v_lshl_or_b32 v2, v209, 16, v207
	v_rcp_f32_e32 v87, v84
	s_nop 0
	v_pk_mul_f32 v[84:85], v[84:85], v[86:87]
	s_nop 0
	v_cvt_pk_bf16_f32 v14, v84, v85
	v_mul_f32_e32 v84, v98, v84
	v_cvt_pk_bf16_f32 v84, v84, s0
	ds_write_b16 v106, v14 offset:1632
	ds_write_b16_d16_hi v106, v14 offset:36448
	ds_write_b16 v113, v84
	v_add_f32_e32 v14, v3, v82
	v_sub_f32_e32 v3, v14, v15
	v_med3_f32 v3, v3, s63, v152
	v_mul_f32_e32 v3, 0x3fb8aa3b, v3
	v_exp_f32_e32 v82, v3
	v_add_f32_e32 v14, v14, v80
	v_sub_f32_e32 v80, v14, v15
	v_med3_f32 v80, v80, s63, v152
	v_rcp_f32_e32 v85, v82
	v_mul_f32_e32 v80, 0x3fb8aa3b, v80
	v_exp_f32_e32 v80, v80
	s_waitcnt vmcnt(49)
; __device__ __forceinline__ unsigned cvtpk_s(float lo, float hi) { f32x2_t v = {lo, hi}; bf16x2_t b = __builtin_convertvector(v, bf16x2_t); return __builtin_bit_cast(unsigned, b); }
; __global__ void __launch_bounds__(NT, 2) hymba_fwd(Args args) {
;     ...
;             for (int i = 0; i < 32; ++i) { const int s = 32 * seg + i;
;                 run += lf[i]; const float q = bf2f((unsigned short)qr[i]);
;                 { const float e1 = __expf(fminf(fmaxf(run - ref, -80.f), 80.f)), qt = q * e1; const unsigned pa = cvtpk_s(qt, kk[i] * __builtin_amdgcn_rcpf(e1)), pb = cvtpk_s(qt * eref, 0.f); X0[s * XP + d] = (bf16)pa; X1[s * XP + d] = (bf16)(pa >> 16); X2[s * XP + d] = (bf16)pb; }
;                 const unsigned v = vr[i]; if (i & 1) vp[i >> 1] |= v << 16; else vp[i >> 1] = v; }
	v_lshlrev_b32_e32 v84, 16, v206
	v_add_f32_e32 v14, v14, v4
	v_pk_mul_f32 v[82:83], v[82:83], v[84:85]
	v_sub_f32_e32 v4, v14, v15
	v_cvt_pk_bf16_f32 v3, v82, v83
	v_rcp_f32_e32 v83, v80
	v_med3_f32 v4, v4, s63, v152
	v_mul_f32_e32 v82, v98, v82
	v_mul_f32_e32 v4, 0x3fb8aa3b, v4
	v_cvt_pk_bf16_f32 v82, v82, s0
	v_exp_f32_e32 v4, v4
	ds_write_b16 v106, v3 offset:1904
	ds_write_b16_d16_hi v106, v3 offset:36720
	ds_write_b16 v114, v82
	s_waitcnt vmcnt(47)
	v_lshlrev_b32_e32 v82, 16, v204
	v_pk_mul_f32 v[80:81], v[80:81], v[82:83]
	v_lshl_or_b32 v3, v205, 16, v203
	v_cvt_pk_bf16_f32 v81, v80, v81
	v_mul_f32_e32 v80, v98, v80
	v_cvt_pk_bf16_f32 v80, v80, s0
	ds_write_b16 v106, v81 offset:2176
	ds_write_b16_d16_hi v106, v81 offset:36992
	ds_write_b16 v115, v80
	v_rcp_f32_e32 v81, v4
	s_waitcnt vmcnt(45)
	v_lshlrev_b32_e32 v80, 16, v202
	v_pk_mul_f32 v[4:5], v[4:5], v[80:81]
	s_nop 0
	v_cvt_pk_bf16_f32 v5, v4, v5
	v_mul_f32_e32 v4, v98, v4
	v_cvt_pk_bf16_f32 v4, v4, s0
	ds_write_b16 v106, v5 offset:2448
	ds_write_b16_d16_hi v106, v5 offset:37264
	ds_write_b16 v116, v4
	v_add_f32_e32 v5, v14, v78
	v_sub_f32_e32 v14, v5, v15
	v_med3_f32 v14, v14, s63, v152
	v_mul_f32_e32 v14, 0x3fb8aa3b, v14
	v_exp_f32_e32 v78, v14
	s_waitcnt vmcnt(43)
	v_lshlrev_b32_e32 v80, 16, v200
	v_lshl_or_b32 v4, v201, 16, v199
	v_rcp_f32_e32 v81, v78
	s_nop 0
	v_pk_mul_f32 v[78:79], v[78:79], v[80:81]
	s_nop 0
	v_cvt_pk_bf16_f32 v14, v78, v79
	v_mul_f32_e32 v78, v98, v78
	v_cvt_pk_bf16_f32 v78, v78, s0
	ds_write_b16 v106, v14 offset:2720
	ds_write_b16_d16_hi v106, v14 offset:37536
	ds_write_b16 v117, v78
	v_add_f32_e32 v14, v5, v76
	v_sub_f32_e32 v5, v14, v15
	v_med3_f32 v5, v5, s63, v152
	v_mul_f32_e32 v5, 0x3fb8aa3b, v5
	v_exp_f32_e32 v76, v5
	v_add_f32_e32 v14, v14, v74
	v_sub_f32_e32 v74, v14, v15
	v_med3_f32 v74, v74, s63, v152
	v_rcp_f32_e32 v79, v76
	v_mul_f32_e32 v74, 0x3fb8aa3b, v74
	v_exp_f32_e32 v74, v74
	s_waitcnt vmcnt(41)
	v_lshlrev_b32_e32 v78, 16, v198
	v_add_f32_e32 v14, v14, v6
	v_pk_mul_f32 v[76:77], v[76:77], v[78:79]
	v_sub_f32_e32 v6, v14, v15
	v_cvt_pk_bf16_f32 v5, v76, v77
	v_rcp_f32_e32 v77, v74
	v_med3_f32 v6, v6, s63, v152
	v_mul_f32_e32 v76, v98, v76
	v_mul_f32_e32 v6, 0x3fb8aa3b, v6
	v_cvt_pk_bf16_f32 v76, v76, s0
	v_exp_f32_e32 v6, v6
	ds_write_b16 v106, v5 offset:2992
	ds_write_b16_d16_hi v106, v5 offset:37808
	ds_write_b16 v118, v76
	s_waitcnt vmcnt(39)
	v_lshlrev_b32_e32 v76, 16, v196
	v_pk_mul_f32 v[74:75], v[74:75], v[76:77]
	v_lshl_or_b32 v5, v197, 16, v195
	v_cvt_pk_bf16_f32 v75, v74, v75
	v_mul_f32_e32 v74, v98, v74
	v_cvt_pk_bf16_f32 v74, v74, s0
	ds_write_b16 v106, v75 offset:3264
	ds_write_b16_d16_hi v106, v75 offset:38080
	ds_write_b16 v119, v74
	v_rcp_f32_e32 v75, v6
	s_waitcnt vmcnt(37)
	v_lshlrev_b32_e32 v74, 16, v194
	v_pk_mul_f32 v[6:7], v[6:7], v[74:75]
	s_nop 0
	v_cvt_pk_bf16_f32 v7, v6, v7
	v_mul_f32_e32 v6, v98, v6
	v_cvt_pk_bf16_f32 v6, v6, s0
	ds_write_b16 v106, v7 offset:3536
	ds_write_b16_d16_hi v106, v7 offset:38352
	ds_write_b16 v120, v6
	v_add_f32_e32 v7, v14, v72
	v_sub_f32_e32 v14, v7, v15
	v_med3_f32 v14, v14, s63, v152
	v_mul_f32_e32 v14, 0x3fb8aa3b, v14
	v_exp_f32_e32 v72, v14
	s_waitcnt vmcnt(35)
	v_lshlrev_b32_e32 v74, 16, v192
	v_lshl_or_b32 v6, v193, 16, v191
	v_rcp_f32_e32 v75, v72
	s_nop 0
	v_pk_mul_f32 v[72:73], v[72:73], v[74:75]
	s_nop 0
	v_cvt_pk_bf16_f32 v14, v72, v73
	v_mul_f32_e32 v72, v98, v72
	v_cvt_pk_bf16_f32 v72, v72, s0
	ds_write_b16 v106, v14 offset:3808
	ds_write_b16_d16_hi v106, v14 offset:38624
	ds_write_b16 v121, v72
	v_add_f32_e32 v14, v7, v70
	v_sub_f32_e32 v7, v14, v15
	v_med3_f32 v7, v7, s63, v152
	v_mul_f32_e32 v7, 0x3fb8aa3b, v7
	v_exp_f32_e32 v70, v7
	v_add_f32_e32 v14, v14, v68
	v_sub_f32_e32 v68, v14, v15
	v_med3_f32 v68, v68, s63, v152
	v_rcp_f32_e32 v73, v70
	v_mul_f32_e32 v68, 0x3fb8aa3b, v68
	v_exp_f32_e32 v68, v68
	s_waitcnt vmcnt(33)
	v_lshlrev_b32_e32 v72, 16, v190
	v_add_f32_e32 v14, v14, v8
	v_pk_mul_f32 v[70:71], v[70:71], v[72:73]
	v_sub_f32_e32 v8, v14, v15
	v_cvt_pk_bf16_f32 v7, v70, v71
	v_rcp_f32_e32 v71, v68
	v_med3_f32 v8, v8, s63, v152
	v_mul_f32_e32 v70, v98, v70
	v_mul_f32_e32 v8, 0x3fb8aa3b, v8
	v_cvt_pk_bf16_f32 v70, v70, s0
	v_exp_f32_e32 v8, v8
	ds_write_b16 v106, v7 offset:4080
	ds_write_b16_d16_hi v106, v7 offset:38896
	ds_write_b16 v122, v70
	s_waitcnt vmcnt(31)
	v_lshlrev_b32_e32 v70, 16, v188
	v_pk_mul_f32 v[68:69], v[68:69], v[70:71]
	v_lshl_or_b32 v7, v189, 16, v187
	v_cvt_pk_bf16_f32 v69, v68, v69
	v_mul_f32_e32 v68, v98, v68
	v_cvt_pk_bf16_f32 v68, v68, s0
	ds_write_b16 v106, v69 offset:4352
	ds_write_b16_d16_hi v106, v69 offset:39168
	ds_write_b16 v123, v68
	v_rcp_f32_e32 v69, v8
	s_waitcnt vmcnt(29)
	v_lshlrev_b32_e32 v68, 16, v186
	v_pk_mul_f32 v[8:9], v[8:9], v[68:69]
	s_nop 0
	v_cvt_pk_bf16_f32 v9, v8, v9
	v_mul_f32_e32 v8, v98, v8
	v_cvt_pk_bf16_f32 v8, v8, s0
	ds_write_b16 v106, v9 offset:4624
	ds_write_b16_d16_hi v106, v9 offset:39440
	ds_write_b16 v124, v8
	v_add_f32_e32 v9, v14, v66
	v_sub_f32_e32 v14, v9, v15
	v_med3_f32 v14, v14, s63, v152
	v_mul_f32_e32 v14, 0x3fb8aa3b, v14
	v_exp_f32_e32 v66, v14
	s_waitcnt vmcnt(27)
	v_lshlrev_b32_e32 v68, 16, v184
	v_lshl_or_b32 v8, v185, 16, v183
	v_rcp_f32_e32 v69, v66
	s_nop 0
	v_pk_mul_f32 v[66:67], v[66:67], v[68:69]
	s_nop 0
	v_cvt_pk_bf16_f32 v14, v66, v67
	v_mul_f32_e32 v66, v98, v66
	v_cvt_pk_bf16_f32 v66, v66, s0
	ds_write_b16 v106, v14 offset:4896
	ds_write_b16_d16_hi v106, v14 offset:39712
	ds_write_b16 v125, v66
	v_add_f32_e32 v14, v9, v54
	v_sub_f32_e32 v9, v14, v15
	v_med3_f32 v9, v9, s63, v152
	v_mul_f32_e32 v9, 0x3fb8aa3b, v9
	v_exp_f32_e32 v54, v9
	v_add_f32_e32 v14, v14, v52
	v_sub_f32_e32 v52, v14, v15
	v_med3_f32 v52, v52, s63, v152
	v_rcp_f32_e32 v67, v54
	v_mul_f32_e32 v52, 0x3fb8aa3b, v52
	v_exp_f32_e32 v52, v52
	s_waitcnt vmcnt(25)
; #define LAS __attribute__((address_space(3)))
; __device__ __forceinline__ unsigned cvtpk_s(float lo, float hi) { f32x2_t v = {lo, hi}; bf16x2_t b = __builtin_convertvector(v, bf16x2_t); return __builtin_bit_cast(unsigned, b); }
; __global__ void __launch_bounds__(NT, 2) hymba_fwd(Args args) {
;     ...
;             for (int i = 0; i < 32; ++i) { const int s = 32 * seg + i;
;                 run += lf[i]; const float q = bf2f((unsigned short)qr[i]);
;                 { const float e1 = __expf(fminf(fmaxf(run - ref, -80.f), 80.f)), qt = q * e1; const unsigned pa = cvtpk_s(qt, kk[i] * __builtin_amdgcn_rcpf(e1)), pb = cvtpk_s(qt * eref, 0.f); X0[s * XP + d] = (bf16)pa; X1[s * XP + d] = (bf16)(pa >> 16); X2[s * XP + d] = (bf16)pb; }
;                 const unsigned v = vr[i]; if (i & 1) vp[i >> 1] |= v << 16; else vp[i >> 1] = v; }
;             LAS u32x4* vt = (LAS u32x4*)(lds + 3 * XB + d * (XP * 2) + seg * 64);
; #pragma unroll
;             for (int q = 0; q < 4; ++q) vt[q] = (u32x4){vp[4 * q], vp[4 * q + 1], vp[4 * q + 2], vp[4 * q + 3]};
;             __syncthreads();
	v_lshlrev_b32_e32 v66, 16, v182
	v_add_f32_e32 v14, v14, v10
	v_pk_mul_f32 v[54:55], v[54:55], v[66:67]
	v_sub_f32_e32 v10, v14, v15
	v_cvt_pk_bf16_f32 v9, v54, v55
	v_rcp_f32_e32 v55, v52
	v_med3_f32 v10, v10, s63, v152
	v_mul_f32_e32 v54, v98, v54
	v_mul_f32_e32 v10, 0x3fb8aa3b, v10
	v_cvt_pk_bf16_f32 v54, v54, s0
	v_exp_f32_e32 v10, v10
	ds_write_b16 v106, v9 offset:5168
	ds_write_b16_d16_hi v106, v9 offset:39984
	ds_write_b16 v126, v54
	s_waitcnt vmcnt(23)
	v_lshlrev_b32_e32 v54, 16, v180
	v_pk_mul_f32 v[52:53], v[52:53], v[54:55]
	v_lshl_or_b32 v9, v181, 16, v177
	v_cvt_pk_bf16_f32 v53, v52, v53
	v_mul_f32_e32 v52, v98, v52
	v_cvt_pk_bf16_f32 v52, v52, s0
	ds_write_b16 v106, v53 offset:5440
	ds_write_b16_d16_hi v106, v53 offset:40256
	ds_write_b16 v127, v52
	v_rcp_f32_e32 v53, v10
	s_waitcnt vmcnt(21)
	v_lshlrev_b32_e32 v52, 16, v176
	v_pk_mul_f32 v[10:11], v[10:11], v[52:53]
	s_nop 0
	v_cvt_pk_bf16_f32 v11, v10, v11
	v_mul_f32_e32 v10, v98, v10
	v_cvt_pk_bf16_f32 v10, v10, s0
	ds_write_b16 v106, v11 offset:5712
	ds_write_b16_d16_hi v106, v11 offset:40528
	ds_write_b16 v128, v10
	v_add_f32_e32 v11, v14, v50
	v_sub_f32_e32 v14, v11, v15
	v_med3_f32 v14, v14, s63, v152
	v_mul_f32_e32 v14, 0x3fb8aa3b, v14
	v_exp_f32_e32 v50, v14
	s_waitcnt vmcnt(19)
	v_lshlrev_b32_e32 v52, 16, v174
	v_lshl_or_b32 v10, v175, 16, v173
	v_rcp_f32_e32 v53, v50
	s_nop 0
	v_pk_mul_f32 v[50:51], v[50:51], v[52:53]
	s_nop 0
	v_cvt_pk_bf16_f32 v14, v50, v51
	v_mul_f32_e32 v50, v98, v50
	v_cvt_pk_bf16_f32 v50, v50, s0
	ds_write_b16 v106, v14 offset:5984
	ds_write_b16_d16_hi v106, v14 offset:40800
	ds_write_b16 v129, v50
	v_add_f32_e32 v14, v11, v30
	v_sub_f32_e32 v11, v14, v15
	v_med3_f32 v11, v11, s63, v152
	v_mul_f32_e32 v11, 0x3fb8aa3b, v11
	v_exp_f32_e32 v30, v11
	v_add_f32_e32 v14, v14, v28
	v_sub_f32_e32 v28, v14, v15
	v_med3_f32 v28, v28, s63, v152
	v_rcp_f32_e32 v51, v30
	v_mul_f32_e32 v28, 0x3fb8aa3b, v28
	v_exp_f32_e32 v28, v28
	s_waitcnt vmcnt(17)
	v_lshlrev_b32_e32 v50, 16, v172
	v_add_f32_e32 v14, v14, v12
	v_pk_mul_f32 v[30:31], v[30:31], v[50:51]
	v_sub_f32_e32 v12, v14, v15
	v_cvt_pk_bf16_f32 v11, v30, v31
	v_rcp_f32_e32 v31, v28
	v_med3_f32 v12, v12, s63, v152
	v_mul_f32_e32 v30, v98, v30
	v_mul_f32_e32 v12, 0x3fb8aa3b, v12
	v_cvt_pk_bf16_f32 v30, v30, s0
	v_exp_f32_e32 v12, v12
	ds_write_b16 v106, v11 offset:6256
	ds_write_b16_d16_hi v106, v11 offset:41072
	ds_write_b16 v130, v30
	s_waitcnt vmcnt(15)
	v_lshlrev_b32_e32 v30, 16, v170
	v_pk_mul_f32 v[28:29], v[28:29], v[30:31]
	v_lshl_or_b32 v11, v171, 16, v169
	v_cvt_pk_bf16_f32 v29, v28, v29
	v_mul_f32_e32 v28, v98, v28
	v_cvt_pk_bf16_f32 v28, v28, s0
	ds_write_b16 v106, v29 offset:6528
	ds_write_b16_d16_hi v106, v29 offset:41344
	ds_write_b16 v131, v28
	v_rcp_f32_e32 v29, v12
	s_waitcnt vmcnt(13)
	v_lshlrev_b32_e32 v28, 16, v168
	v_pk_mul_f32 v[12:13], v[12:13], v[28:29]
	s_nop 0
	v_cvt_pk_bf16_f32 v13, v12, v13
	v_mul_f32_e32 v12, v98, v12
	v_cvt_pk_bf16_f32 v12, v12, s0
	ds_write_b16 v106, v13 offset:6800
	ds_write_b16_d16_hi v106, v13 offset:41616
	ds_write_b16 v132, v12
	v_add_f32_e32 v13, v14, v26
	v_sub_f32_e32 v14, v13, v15
	v_med3_f32 v14, v14, s63, v152
	v_mul_f32_e32 v14, 0x3fb8aa3b, v14
	v_exp_f32_e32 v26, v14
	s_waitcnt vmcnt(11)
	v_lshlrev_b32_e32 v28, 16, v166
	v_lshl_or_b32 v12, v167, 16, v165
	v_rcp_f32_e32 v29, v26
	s_nop 0
	v_pk_mul_f32 v[26:27], v[26:27], v[28:29]
	s_nop 0
	v_cvt_pk_bf16_f32 v14, v26, v27
	v_mul_f32_e32 v26, v98, v26
	v_cvt_pk_bf16_f32 v26, v26, s0
	ds_write_b16 v106, v14 offset:7072
	ds_write_b16_d16_hi v106, v14 offset:41888
	ds_write_b16 v133, v26
	v_add_f32_e32 v14, v13, v24
	v_sub_f32_e32 v13, v14, v15
	v_med3_f32 v13, v13, s63, v152
	v_mul_f32_e32 v13, 0x3fb8aa3b, v13
	v_exp_f32_e32 v24, v13
	v_add_f32_e32 v14, v14, v22
	v_sub_f32_e32 v22, v14, v15
	v_med3_f32 v22, v22, s63, v152
	v_rcp_f32_e32 v27, v24
	v_mul_f32_e32 v22, 0x3fb8aa3b, v22
	v_exp_f32_e32 v22, v22
	s_waitcnt vmcnt(9)
	v_lshlrev_b32_e32 v26, 16, v164
	v_pk_mul_f32 v[24:25], v[24:25], v[26:27]
	s_nop 0
	v_cvt_pk_bf16_f32 v13, v24, v25
	v_rcp_f32_e32 v25, v22
	v_mul_f32_e32 v24, v98, v24
	v_cvt_pk_bf16_f32 v24, v24, s0
	ds_write_b16 v106, v13 offset:7344
	ds_write_b16_d16_hi v106, v13 offset:42160
	ds_write_b16 v134, v24
	s_waitcnt vmcnt(7)
	v_lshlrev_b32_e32 v24, 16, v162
	v_pk_mul_f32 v[22:23], v[22:23], v[24:25]
	v_add_f32_e32 v24, v14, v20
	v_sub_f32_e32 v14, v24, v15
	v_med3_f32 v14, v14, s63, v152
	v_mul_f32_e32 v14, 0x3fb8aa3b, v14
	v_exp_f32_e32 v20, v14
	v_cvt_pk_bf16_f32 v23, v22, v23
	v_mul_f32_e32 v22, v98, v22
	v_cvt_pk_bf16_f32 v22, v22, s0
	ds_write_b16 v106, v23 offset:7616
	ds_write_b16_d16_hi v106, v23 offset:42432
	ds_write_b16 v135, v22
	v_rcp_f32_e32 v23, v20
	s_waitcnt vmcnt(5)
	v_lshlrev_b32_e32 v22, 16, v160
	v_lshl_or_b32 v13, v163, 16, v161
	v_pk_mul_f32 v[20:21], v[20:21], v[22:23]
	v_add_f32_e32 v22, v24, v18
	v_sub_f32_e32 v18, v22, v15
	v_med3_f32 v18, v18, s63, v152
	v_mul_f32_e32 v18, 0x3fb8aa3b, v18
	v_exp_f32_e32 v18, v18
	v_add_f32_e32 v16, v22, v16
	v_sub_f32_e32 v15, v16, v15
	v_cvt_pk_bf16_f32 v14, v20, v21
	v_rcp_f32_e32 v21, v18
	v_med3_f32 v15, v15, s63, v152
	v_mul_f32_e32 v20, v98, v20
	v_mul_f32_e32 v15, 0x3fb8aa3b, v15
	v_cvt_pk_bf16_f32 v20, v20, s0
	v_exp_f32_e32 v16, v15
	ds_write_b16 v106, v14 offset:7888
	ds_write_b16_d16_hi v106, v14 offset:42704
	ds_write_b16 v136, v20
	s_waitcnt vmcnt(3)
	v_lshlrev_b32_e32 v20, 16, v158
	v_pk_mul_f32 v[18:19], v[18:19], v[20:21]
	v_lshl_or_b32 v14, v159, 16, v157
	v_cvt_pk_bf16_f32 v19, v18, v19
	v_mul_f32_e32 v18, v98, v18
	v_cvt_pk_bf16_f32 v18, v18, s0
	ds_write_b16 v106, v19 offset:8160
	ds_write_b16_d16_hi v106, v19 offset:42976
	ds_write_b16 v137, v18
	v_rcp_f32_e32 v19, v16
	s_waitcnt vmcnt(1)
	v_lshlrev_b32_e32 v18, 16, v99
	v_pk_mul_f32 v[16:17], v[16:17], v[18:19]
	s_nop 0
	v_cvt_pk_bf16_f32 v15, v16, v17
	v_mul_f32_e32 v16, v98, v16
	v_cvt_pk_bf16_f32 v16, v16, s0
	ds_write_b16 v106, v15 offset:8432
	ds_write_b16_d16_hi v106, v15 offset:43248
	ds_write_b16 v138, v16
	s_waitcnt vmcnt(0)
	v_lshl_or_b32 v15, v97, 16, v96
	ds_write_b128 v140, v[0:3]
	ds_write_b128 v140, v[4:7] offset:16
	ds_write_b128 v140, v[8:11] offset:32
	ds_write_b128 v140, v[12:15] offset:48
	s_waitcnt lgkmcnt(0)
	s_barrier
; #define LAS __attribute__((address_space(3)))
; __device__ __forceinline__ unsigned f2bf(float f) { unsigned u = __builtin_bit_cast(unsigned, f); return (u + 0x7fffu + ((u >> 16) & 1u)) >> 16; }
; __device__ __forceinline__ int crow(int r, int hi) { return (r & 3) + 8 * (r >> 2) + 4 * hi; }
; __global__ void __launch_bounds__(NT, 2) hymba_fwd(Args args) {
;     ...
;             f32x16 acc[2];
; #pragma unroll
;             for (int r = 0; r < 16; ++r) { acc[0][r] = 0.f; acc[1][r] = 0.f; }
;             mm128(lds + 0 * XB, lds + 1 * XB, acc, wave, lane);
;             __syncthreads();
;             { const int l32 = lane & 31, hh = lane >> 5;
; #pragma unroll
;               for (int nt = 0; nt < 2; ++nt)
; #pragma unroll
;                 for (int r = 0; r < 16; ++r) { const int t = (wave & 3) * 32 + crow(r, hh), s = (wave >> 2) * 64 + 32 * nt + l32; X0[t * XP + s] = (bf16)(s <= t ? f2bf(acc[nt][r]) : 0u); } }
;             {
; #pragma unroll
;               for (int q = 0; q < 4; ++q) { const int e = (q * NT + tid) * 8, rr = e >> 7, cc = e & 127; *(LAS u32x4*)(X1 + rr * XP + cc) = *(const u32x4*)(DST + (size_t)((c - 1) * 4 + h) * 16384 + e); } }
	ds_read_b128 v[0:3], v154 offset:43520
	ds_read_b128 v[4:7], v153
	ds_read_b128 v[50:53], v153 offset:32
	ds_read_b128 v[8:11], v154 offset:34816
	ds_read_b128 v[66:69], v154 offset:34848
	s_waitcnt lgkmcnt(1)
	v_mfma_f32_32x32x16_bf16 v[16:31], v[4:7], v[8:11], 0
	ds_read_b128 v[70:73], v154 offset:43552
	v_mfma_f32_32x32x16_bf16 v[0:15], v[4:7], v[0:3], 0
	s_waitcnt lgkmcnt(1)
	v_mfma_f32_32x32x16_bf16 v[16:31], v[50:53], v[66:69], v[16:31]
	s_waitcnt lgkmcnt(0)
	v_mfma_f32_32x32x16_bf16 v[0:15], v[50:53], v[70:73], v[0:15]
	ds_read_b128 v[50:53], v153 offset:64
	ds_read_b128 v[66:69], v154 offset:34880
	ds_read_b128 v[70:73], v154 offset:43584
	s_waitcnt lgkmcnt(1)
	v_mfma_f32_32x32x16_bf16 v[16:31], v[50:53], v[66:69], v[16:31]
	s_waitcnt lgkmcnt(0)
	v_mfma_f32_32x32x16_bf16 v[0:15], v[50:53], v[70:73], v[0:15]
	ds_read_b128 v[50:53], v153 offset:96
	ds_read_b128 v[66:69], v154 offset:34912
	ds_read_b128 v[70:73], v154 offset:43616
	s_waitcnt lgkmcnt(1)
	v_mfma_f32_32x32x16_bf16 v[16:31], v[50:53], v[66:69], v[16:31]
	s_waitcnt lgkmcnt(0)
	v_mfma_f32_32x32x16_bf16 v[0:15], v[50:53], v[70:73], v[0:15]
	ds_read_b128 v[50:53], v153 offset:128
	ds_read_b128 v[66:69], v154 offset:34944
	ds_read_b128 v[70:73], v154 offset:43648
	s_waitcnt lgkmcnt(1)
	v_mfma_f32_32x32x16_bf16 v[16:31], v[50:53], v[66:69], v[16:31]
	s_waitcnt lgkmcnt(0)
	v_mfma_f32_32x32x16_bf16 v[0:15], v[50:53], v[70:73], v[0:15]
	ds_read_b128 v[50:53], v153 offset:160
	ds_read_b128 v[66:69], v154 offset:34976
	ds_read_b128 v[70:73], v154 offset:43680
	s_waitcnt lgkmcnt(1)
	v_mfma_f32_32x32x16_bf16 v[16:31], v[50:53], v[66:69], v[16:31]
	s_waitcnt lgkmcnt(0)
	v_mfma_f32_32x32x16_bf16 v[0:15], v[50:53], v[70:73], v[0:15]
	ds_read_b128 v[50:53], v153 offset:192
	ds_read_b128 v[66:69], v154 offset:35008
	ds_read_b128 v[70:73], v154 offset:43712
	s_waitcnt lgkmcnt(1)
	v_mfma_f32_32x32x16_bf16 v[16:31], v[50:53], v[66:69], v[16:31]
	s_waitcnt lgkmcnt(0)
	v_mfma_f32_32x32x16_bf16 v[0:15], v[50:53], v[70:73], v[0:15]
	ds_read_b128 v[50:53], v153 offset:224
	ds_read_b128 v[66:69], v154 offset:35040
	ds_read_b128 v[70:73], v154 offset:43744
	s_waitcnt lgkmcnt(0)
	s_barrier
	s_mov_b32 s98, 0xffffa000
	s_mov_b32 s99, -1
	v_lshl_add_u64 v[204:205], v[64:65], 0, s[98:99]
	global_load_dwordx4 v[160:163], v[204:205], off
	s_mov_b32 s98, 0xffffc000
	v_lshl_add_u64 v[204:205], v[64:65], 0, s[98:99]
	global_load_dwordx4 v[164:167], v[204:205], off
	s_mov_b32 s98, 0xffffe000
	v_lshl_add_u64 v[204:205], v[64:65], 0, s[98:99]
	global_load_dwordx4 v[168:171], v[204:205], off
	global_load_dwordx4 v[172:175], v[64:65], off
	v_mfma_f32_32x32x16_bf16 v[16:31], v[50:53], v[66:69], v[16:31]
	v_mfma_f32_32x32x16_bf16 v[0:15], v[50:53], v[70:73], v[0:15]
	s_and_saveexec_b64 s[0:1], s[48:49]
	s_nop 9
	v_bfe_u32 v50, v16, 16, 1
	v_add3_u32 v16, v16, v50, s64
	v_lshrrev_b32_e32 v156, 16, v16
	s_or_b64 exec, exec, s[0:1]
	v_mov_b32_e32 v16, 0
	v_mov_b32_e32 v50, 0
	ds_write_b16 v155, v156
	s_and_saveexec_b64 s[0:1], s[40:41]
	v_readlane_b32 s2, v237, 27
	v_readlane_b32 s3, v237, 28
	v_bfe_u32 v50, v17, 16, 1
	v_add3_u32 v17, v17, v50, s64
	v_lshrrev_b32_e32 v50, 16, v17
	s_or_b64 exec, exec, s[0:1]
	ds_write_b16 v155, v50 offset:272
	s_and_saveexec_b64 s[0:1], s[42:43]
	v_bfe_u32 v16, v18, 16, 1
	v_add3_u32 v16, v18, v16, s64
	v_lshrrev_b32_e32 v16, 16, v16
	s_or_b64 exec, exec, s[0:1]
	ds_write_b16 v155, v16 offset:544
	v_mov_b32_e32 v16, 0
	v_mov_b32_e32 v17, 0
	s_and_saveexec_b64 s[0:1], s[54:55]
	v_bfe_u32 v17, v19, 16, 1
	v_add3_u32 v17, v19, v17, s64
	v_lshrrev_b32_e32 v17, 16, v17
	s_or_b64 exec, exec, s[0:1]
	ds_write_b16 v155, v17 offset:816
	s_and_saveexec_b64 s[0:1], s[56:57]
	v_bfe_u32 v16, v20, 16, 1
	v_add3_u32 v16, v20, v16, s64
	v_lshrrev_b32_e32 v16, 16, v16
	s_or_b64 exec, exec, s[0:1]
	ds_write_b16 v155, v16 offset:2176
	v_mov_b32_e32 v16, 0
	v_mov_b32_e32 v17, 0
	s_and_saveexec_b64 s[0:1], s[46:47]
	v_bfe_u32 v17, v21, 16, 1
	v_add3_u32 v17, v21, v17, s64
	v_lshrrev_b32_e32 v17, 16, v17
	s_or_b64 exec, exec, s[0:1]
	ds_write_b16 v155, v17 offset:2448
	s_mov_b64 s[0:1], exec
	v_readlane_b32 s4, v237, 48
	v_readlane_b32 s5, v237, 49
	s_and_b64 s[4:5], s[0:1], s[4:5]
	s_mov_b64 exec, s[4:5]
	v_bfe_u32 v16, v22, 16, 1
	v_add3_u32 v16, v22, v16, s64
	v_lshrrev_b32_e32 v16, 16, v16
	s_or_b64 exec, exec, s[0:1]
	ds_write_b16 v155, v16 offset:2720
	v_mov_b32_e32 v16, 0
	v_mov_b32_e32 v17, 0
	s_mov_b64 s[0:1], exec
	v_readlane_b32 s4, v237, 42
	v_readlane_b32 s5, v237, 43
	s_and_b64 s[4:5], s[0:1], s[4:5]
	s_mov_b64 exec, s[4:5]
	v_bfe_u32 v17, v23, 16, 1
	v_add3_u32 v17, v23, v17, s64
	v_lshrrev_b32_e32 v17, 16, v17
	s_or_b64 exec, exec, s[0:1]
	ds_write_b16 v155, v17 offset:2992
	s_mov_b64 s[0:1], exec
	v_readlane_b32 s4, v237, 57
	v_readlane_b32 s5, v237, 58
	s_and_b64 s[4:5], s[0:1], s[4:5]
	s_mov_b64 exec, s[4:5]
	v_bfe_u32 v16, v24, 16, 1
	v_add3_u32 v16, v24, v16, s64
	v_lshrrev_b32_e32 v16, 16, v16
	s_or_b64 exec, exec, s[0:1]
	ds_write_b16 v155, v16 offset:4352
	v_mov_b32_e32 v16, 0
	v_mov_b32_e32 v17, 0
	s_mov_b64 s[0:1], exec
	v_readlane_b32 s4, v237, 59
	v_readlane_b32 s5, v237, 60
	s_and_b64 s[4:5], s[0:1], s[4:5]
	s_mov_b64 exec, s[4:5]
	v_bfe_u32 v17, v25, 16, 1
	v_add3_u32 v17, v25, v17, s64
	v_lshrrev_b32_e32 v17, 16, v17
	s_or_b64 exec, exec, s[0:1]
	ds_write_b16 v155, v17 offset:4624
	s_mov_b64 s[0:1], exec
	v_readlane_b32 s4, v237, 61
	v_readlane_b32 s5, v237, 62
	s_and_b64 s[4:5], s[0:1], s[4:5]
	s_mov_b64 exec, s[4:5]
	v_bfe_u32 v16, v26, 16, 1
	v_add3_u32 v16, v26, v16, s64
	v_lshrrev_b32_e32 v16, 16, v16
	s_or_b64 exec, exec, s[0:1]
	ds_write_b16 v155, v16 offset:4896
; __device__ __forceinline__ unsigned f2bf(float f) { unsigned u = __builtin_bit_cast(unsigned, f); return (u + 0x7fffu + ((u >> 16) & 1u)) >> 16; }
; __device__ __forceinline__ int crow(int r, int hi) { return (r & 3) + 8 * (r >> 2) + 4 * hi; }
; __global__ void __launch_bounds__(NT, 2) hymba_fwd(Args args) {
;     ...
;             { const int l32 = lane & 31, hh = lane >> 5;
; #pragma unroll
;               for (int nt = 0; nt < 2; ++nt)
; #pragma unroll
;                 for (int r = 0; r < 16; ++r) { const int t = (wave & 3) * 32 + crow(r, hh), s = (wave >> 2) * 64 + 32 * nt + l32; X0[t * XP + s] = (bf16)(s <= t ? f2bf(acc[nt][r]) : 0u); } }
	v_mov_b32_e32 v16, 0
	v_mov_b32_e32 v17, 0
	s_mov_b64 s[0:1], exec
	v_readlane_b32 s4, v237, 63
	v_readlane_b32 s5, v236, 0
	s_and_b64 s[4:5], s[0:1], s[4:5]
	s_mov_b64 exec, s[4:5]
	v_bfe_u32 v17, v27, 16, 1
	v_add3_u32 v17, v27, v17, s64
	v_lshrrev_b32_e32 v17, 16, v17
	s_or_b64 exec, exec, s[0:1]
	ds_write_b16 v155, v17 offset:5168
	s_mov_b64 s[0:1], exec
	v_readlane_b32 s4, v236, 1
	v_readlane_b32 s5, v236, 2
	s_and_b64 s[4:5], s[0:1], s[4:5]
	s_mov_b64 exec, s[4:5]
	v_bfe_u32 v16, v28, 16, 1
	v_add3_u32 v16, v28, v16, s64
	v_lshrrev_b32_e32 v16, 16, v16
	s_or_b64 exec, exec, s[0:1]
	ds_write_b16 v155, v16 offset:6528
	v_mov_b32_e32 v16, 0
	v_mov_b32_e32 v17, 0
	s_mov_b64 s[0:1], exec
	v_readlane_b32 s4, v236, 3
	v_readlane_b32 s5, v236, 4
	s_and_b64 s[4:5], s[0:1], s[4:5]
	s_mov_b64 exec, s[4:5]
	v_bfe_u32 v17, v29, 16, 1
	v_add3_u32 v17, v29, v17, s64
	v_lshrrev_b32_e32 v17, 16, v17
	s_or_b64 exec, exec, s[0:1]
	ds_write_b16 v155, v17 offset:6800
	s_mov_b64 s[0:1], exec
	v_readlane_b32 s4, v236, 5
	v_readlane_b32 s5, v236, 6
	s_and_b64 s[4:5], s[0:1], s[4:5]
	s_mov_b64 exec, s[4:5]
	v_bfe_u32 v16, v30, 16, 1
	v_add3_u32 v16, v30, v16, s64
	v_lshrrev_b32_e32 v16, 16, v16
	s_or_b64 exec, exec, s[0:1]
	ds_write_b16 v155, v16 offset:7072
	v_mov_b32_e32 v16, 0
	v_mov_b32_e32 v17, 0
	s_mov_b64 s[0:1], exec
	v_readlane_b32 s4, v236, 7
	v_readlane_b32 s5, v236, 8
	s_and_b64 s[4:5], s[0:1], s[4:5]
	s_mov_b64 exec, s[4:5]
	v_bfe_u32 v17, v31, 16, 1
	v_add3_u32 v17, v31, v17, s64
	v_lshrrev_b32_e32 v17, 16, v17
	s_or_b64 exec, exec, s[0:1]
	ds_write_b16 v155, v17 offset:7344
	s_mov_b64 s[0:1], exec
	v_readlane_b32 s4, v236, 9
	v_readlane_b32 s5, v236, 10
	s_and_b64 s[4:5], s[0:1], s[4:5]
	s_mov_b64 exec, s[4:5]
	v_bfe_u32 v16, v0, 16, 1
	v_add3_u32 v0, v0, v16, s64
	v_lshrrev_b32_e32 v16, 16, v0
	s_or_b64 exec, exec, s[0:1]
	ds_write_b16 v155, v16 offset:64
	v_mov_b32_e32 v0, 0
	v_mov_b32_e32 v16, 0
	s_mov_b64 s[0:1], exec
	v_readlane_b32 s4, v236, 11
	v_readlane_b32 s5, v236, 12
	s_and_b64 s[4:5], s[0:1], s[4:5]
	s_mov_b64 exec, s[4:5]
	v_bfe_u32 v16, v1, 16, 1
	v_add3_u32 v1, v1, v16, s64
	v_lshrrev_b32_e32 v16, 16, v1
	s_or_b64 exec, exec, s[0:1]
	ds_write_b16 v155, v16 offset:336
	s_mov_b64 s[0:1], exec
	v_readlane_b32 s4, v236, 13
	v_readlane_b32 s5, v236, 14
	s_and_b64 s[4:5], s[0:1], s[4:5]
	s_mov_b64 exec, s[4:5]
	v_bfe_u32 v0, v2, 16, 1
	v_add3_u32 v0, v2, v0, s64
	v_lshrrev_b32_e32 v0, 16, v0
	s_or_b64 exec, exec, s[0:1]
	ds_write_b16 v155, v0 offset:608
	v_mov_b32_e32 v0, 0
	v_mov_b32_e32 v1, 0
	s_mov_b64 s[0:1], exec
	v_readlane_b32 s4, v236, 15
	v_readlane_b32 s5, v236, 16
	s_and_b64 s[4:5], s[0:1], s[4:5]
	s_mov_b64 exec, s[4:5]
	v_bfe_u32 v1, v3, 16, 1
	v_add3_u32 v1, v3, v1, s64
	v_lshrrev_b32_e32 v1, 16, v1
	s_or_b64 exec, exec, s[0:1]
	ds_write_b16 v155, v1 offset:880
	s_mov_b64 s[0:1], exec
	v_readlane_b32 s4, v236, 17
	v_readlane_b32 s5, v236, 18
	s_and_b64 s[4:5], s[0:1], s[4:5]
	s_mov_b64 exec, s[4:5]
	v_bfe_u32 v0, v4, 16, 1
	v_add3_u32 v0, v4, v0, s64
	v_lshrrev_b32_e32 v0, 16, v0
	s_or_b64 exec, exec, s[0:1]
	ds_write_b16 v155, v0 offset:2240
	v_mov_b32_e32 v0, 0
	v_mov_b32_e32 v1, 0
	s_mov_b64 s[0:1], exec
	v_readlane_b32 s4, v236, 19
	v_readlane_b32 s5, v236, 20
	s_and_b64 s[4:5], s[0:1], s[4:5]
	s_mov_b64 exec, s[4:5]
	v_bfe_u32 v1, v5, 16, 1
	v_add3_u32 v1, v5, v1, s64
	v_lshrrev_b32_e32 v1, 16, v1
	s_or_b64 exec, exec, s[0:1]
	ds_write_b16 v155, v1 offset:2512
	s_mov_b64 s[0:1], exec
	v_readlane_b32 s4, v236, 21
	v_readlane_b32 s5, v236, 22
	s_and_b64 s[4:5], s[0:1], s[4:5]
	s_mov_b64 exec, s[4:5]
	v_bfe_u32 v0, v6, 16, 1
	v_add3_u32 v0, v6, v0, s64
	v_lshrrev_b32_e32 v0, 16, v0
	s_or_b64 exec, exec, s[0:1]
	ds_write_b16 v155, v0 offset:2784
	v_mov_b32_e32 v0, 0
	v_mov_b32_e32 v1, 0
	s_mov_b64 s[0:1], exec
	v_readlane_b32 s4, v236, 23
	v_readlane_b32 s5, v236, 24
	s_and_b64 s[4:5], s[0:1], s[4:5]
	s_mov_b64 exec, s[4:5]
	v_bfe_u32 v1, v7, 16, 1
	v_add3_u32 v1, v7, v1, s64
	v_lshrrev_b32_e32 v1, 16, v1
	s_or_b64 exec, exec, s[0:1]
	ds_write_b16 v155, v1 offset:3056
	s_mov_b64 s[0:1], exec
	v_readlane_b32 s4, v236, 25
	v_readlane_b32 s5, v236, 26
	s_and_b64 s[4:5], s[0:1], s[4:5]
	s_mov_b64 exec, s[4:5]
	v_bfe_u32 v0, v8, 16, 1
	v_add3_u32 v0, v8, v0, s64
	v_lshrrev_b32_e32 v0, 16, v0
	s_or_b64 exec, exec, s[0:1]
	ds_write_b16 v155, v0 offset:4416
	v_mov_b32_e32 v0, 0
	v_mov_b32_e32 v1, 0
	s_mov_b64 s[0:1], exec
	v_readlane_b32 s4, v236, 27
	v_readlane_b32 s5, v236, 28
	s_and_b64 s[4:5], s[0:1], s[4:5]
	s_mov_b64 exec, s[4:5]
	v_bfe_u32 v1, v9, 16, 1
	v_add3_u32 v1, v9, v1, s64
	v_lshrrev_b32_e32 v1, 16, v1
	s_or_b64 exec, exec, s[0:1]
	ds_write_b16 v155, v1 offset:4688
	s_mov_b64 s[0:1], exec
	v_readlane_b32 s4, v236, 29
	v_readlane_b32 s5, v236, 30
	s_and_b64 s[4:5], s[0:1], s[4:5]
	s_mov_b64 exec, s[4:5]
	v_bfe_u32 v0, v10, 16, 1
	v_add3_u32 v0, v10, v0, s64
	v_lshrrev_b32_e32 v0, 16, v0
	s_or_b64 exec, exec, s[0:1]
	ds_write_b16 v155, v0 offset:4960
	v_mov_b32_e32 v0, 0
	v_mov_b32_e32 v1, 0
	s_mov_b64 s[0:1], exec
	v_readlane_b32 s4, v236, 31
	v_readlane_b32 s5, v236, 32
	s_and_b64 s[4:5], s[0:1], s[4:5]
	s_mov_b64 exec, s[4:5]
	v_bfe_u32 v1, v11, 16, 1
	v_add3_u32 v1, v11, v1, s64
	v_lshrrev_b32_e32 v1, 16, v1
	s_or_b64 exec, exec, s[0:1]
	ds_write_b16 v155, v1 offset:5232
	s_mov_b64 s[0:1], exec
	v_readlane_b32 s4, v236, 33
	v_readlane_b32 s5, v236, 34
	s_and_b64 s[4:5], s[0:1], s[4:5]
	s_mov_b64 exec, s[4:5]
	v_bfe_u32 v0, v12, 16, 1
	v_add3_u32 v0, v12, v0, s64
	v_lshrrev_b32_e32 v0, 16, v0
	s_or_b64 exec, exec, s[0:1]
	ds_write_b16 v155, v0 offset:6592
	v_mov_b32_e32 v0, 0
	v_mov_b32_e32 v1, 0
	s_mov_b64 s[0:1], exec
	v_readlane_b32 s4, v236, 35
	v_readlane_b32 s5, v236, 36
	s_and_b64 s[4:5], s[0:1], s[4:5]
	s_mov_b64 exec, s[4:5]
	v_bfe_u32 v1, v13, 16, 1
	v_add3_u32 v1, v13, v1, s64
	v_lshrrev_b32_e32 v1, 16, v1
	s_or_b64 exec, exec, s[0:1]
	ds_write_b16 v155, v1 offset:6864
	s_mov_b64 s[0:1], exec
	v_readlane_b32 s4, v236, 37
	v_readlane_b32 s5, v236, 38
	s_and_b64 s[4:5], s[0:1], s[4:5]
	s_mov_b64 exec, s[4:5]
	v_bfe_u32 v0, v14, 16, 1
	v_add3_u32 v0, v14, v0, s64
	v_lshrrev_b32_e32 v0, 16, v0
	s_or_b64 exec, exec, s[0:1]
	ds_write_b16 v155, v0 offset:7136
	v_mov_b32_e32 v0, 0
	s_mov_b64 s[0:1], exec
	v_readlane_b32 s4, v236, 43
	v_readlane_b32 s5, v236, 44
	s_and_b64 s[4:5], s[0:1], s[4:5]
	s_mov_b64 exec, s[4:5]
	s_cbranch_execz .LBB0_1120
	v_bfe_u32 v0, v15, 16, 1
	v_add3_u32 v0, v15, v0, s64
	v_lshrrev_b32_e32 v0, 16, v0
	s_branch .LBB0_1120
